# neighbourhood attention: the 32 exec-masked LDS bias lookups per tile issued together with one wait, applied by v_cndmask with the same lane masks
# speedup vs baseline: 1.0043x; 1.0043x over previous
.LBB0_943:
	s_add_i32 s69, s6, s5
	s_cmp_ge_u32 s69, s42
	s_cselect_b64 s[56:57], -1, 0
	s_cmp_lt_u32 s69, s43
	s_cselect_b64 s[70:71], -1, 0
	s_and_b64 s[56:57], s[56:57], s[70:71]
	s_andn2_b64 vcc, exec, s[56:57]
	s_cbranch_vccnz .LBB0_940
	ds_read_b128 v[64:67], v145
	ds_read_b128 v[146:149], v145 offset:4608
	s_waitcnt lgkmcnt(1)
	v_mfma_f32_32x32x16_bf16 v[80:95], v[64:67], v[108:111], v[0:15]
	s_waitcnt lgkmcnt(0)
	v_mfma_f32_32x32x16_bf16 v[64:79], v[146:149], v[108:111], v[0:15]
	ds_read_b128 v[146:149], v145 offset:32
	s_waitcnt lgkmcnt(0)
	v_mfma_f32_32x32x16_bf16 v[80:95], v[146:149], v[104:107], v[80:95]
	ds_read_b128 v[146:149], v145 offset:4640
	s_waitcnt lgkmcnt(0)
	v_mfma_f32_32x32x16_bf16 v[64:79], v[146:149], v[104:107], v[64:79]
	ds_read_b128 v[146:149], v145 offset:64
	s_waitcnt lgkmcnt(0)
	v_mfma_f32_32x32x16_bf16 v[80:95], v[146:149], v[100:103], v[80:95]
	ds_read_b128 v[146:149], v145 offset:4672
	s_waitcnt lgkmcnt(0)
	v_mfma_f32_32x32x16_bf16 v[64:79], v[146:149], v[100:103], v[64:79]
	ds_read_b128 v[146:149], v145 offset:96
	s_waitcnt lgkmcnt(0)
	v_mfma_f32_32x32x16_bf16 v[80:95], v[146:149], v[96:99], v[80:95]
	ds_read_b128 v[148:151], v145 offset:4704
	v_mov_b32_e32 v146, 0xf149f2ca
	v_mov_b32_e32 v147, 0xf149f2ca
	s_waitcnt lgkmcnt(0)
	v_mfma_f32_32x32x16_bf16 v[64:79], v[148:151], v[96:99], v[64:79]
	ds_read_b32 v178, v131
	ds_read_b32 v179, v131 offset:128
	ds_read_b32 v180, v131 offset:4
	ds_read_b32 v181, v131 offset:132
	ds_read_b32 v182, v131 offset:8
	ds_read_b32 v183, v131 offset:136
	ds_read_b32 v184, v131 offset:12
	ds_read_b32 v185, v131 offset:140
	ds_read_b32 v186, v131 offset:16
	ds_read_b32 v187, v131 offset:144
	ds_read_b32 v188, v131 offset:20
	ds_read_b32 v189, v131 offset:148
	ds_read_b32 v190, v131 offset:24
	ds_read_b32 v191, v131 offset:152
	ds_read_b32 v192, v131 offset:28
	ds_read_b32 v193, v131 offset:156
	ds_read_b32 v194, v131 offset:64
	ds_read_b32 v195, v131 offset:192
	ds_read_b32 v196, v131 offset:68
	ds_read_b32 v197, v131 offset:196
	ds_read_b32 v198, v131 offset:72
	ds_read_b32 v199, v131 offset:200
	ds_read_b32 v200, v131 offset:76
	ds_read_b32 v201, v131 offset:204
	ds_read_b32 v202, v131 offset:80
	ds_read_b32 v203, v131 offset:208
	ds_read_b32 v204, v131 offset:84
	ds_read_b32 v205, v131 offset:212
	ds_read_b32 v206, v131 offset:88
	ds_read_b32 v207, v131 offset:216
	ds_read_b32 v208, v131 offset:92
	ds_read_b32 v209, v131 offset:220
	s_waitcnt lgkmcnt(0)
	v_add_f32_e32 v178, v80, v178
	v_cndmask_b32_e64 v147, v147, v178, s[0:1]
	v_add_f32_e32 v179, v64, v179
	v_cndmask_b32_e64 v146, v146, v179, s[16:17]
	s_nop 0
	v_mov_b32_e32 v80, 0xf149f2ca
	v_mov_b32_e32 v148, 0xf149f2ca
	v_add_f32_e32 v180, v81, v180
	v_cndmask_b32_e64 v148, v148, v180, s[54:55]
	v_add_f32_e32 v181, v65, v181
	v_cndmask_b32_e64 v80, v80, v181, s[18:19]
	v_mov_b32_e32 v65, 0xf149f2ca
	v_mov_b32_e32 v149, 0xf149f2ca
	v_add_f32_e32 v182, v82, v182
	v_cndmask_b32_e64 v149, v149, v182, s[96:97]
	v_add_f32_e32 v183, v66, v183
	v_cndmask_b32_e64 v65, v65, v183, s[20:21]
	v_mov_b32_e32 v66, 0xf149f2ca
	v_mov_b32_e32 v150, 0xf149f2ca
	v_add_f32_e32 v184, v83, v184
	v_cndmask_b32_e64 v150, v150, v184, s[78:79]
	v_add_f32_e32 v185, v67, v185
	v_cndmask_b32_e64 v66, v66, v185, s[82:83]
	v_mov_b32_e32 v67, 0xf149f2ca
	v_mov_b32_e32 v151, 0xf149f2ca
	v_add_f32_e32 v186, v84, v186
	v_cndmask_b32_e64 v151, v151, v186, s[2:3]
	v_add_f32_e32 v187, v68, v187
	v_cndmask_b32_e64 v67, v67, v187, s[84:85]
	v_mov_b32_e32 v68, 0xf149f2ca
	v_mov_b32_e32 v84, 0xf149f2ca
	v_add_f32_e32 v188, v85, v188
	v_cndmask_b32_e64 v84, v84, v188, s[64:65]
	v_add_f32_e32 v189, v69, v189
	v_cndmask_b32_e64 v68, v68, v189, s[86:87]
	v_mov_b32_e32 v69, 0xf149f2ca
	v_mov_b32_e32 v152, 0xf149f2ca
	v_add_f32_e32 v190, v86, v190
	v_cndmask_b32_e64 v152, v152, v190, s[74:75]
	v_add_f32_e32 v191, v70, v191
	v_cndmask_b32_e64 v69, v69, v191, s[88:89]
	v_mov_b32_e32 v70, 0xf149f2ca
	v_mov_b32_e32 v153, 0xf149f2ca
	v_add_f32_e32 v192, v87, v192
	v_cndmask_b32_e64 v153, v153, v192, s[80:81]
	v_add_f32_e32 v193, v71, v193
	v_cndmask_b32_e64 v70, v70, v193, s[90:91]
	v_mov_b32_e32 v81, 0xf149f2ca
	v_mov_b32_e32 v85, 0xf149f2ca
	v_add_f32_e32 v194, v88, v194
	v_cndmask_b32_e64 v85, v85, v194, s[92:93]
	v_add_f32_e32 v195, v72, v195
	v_cndmask_b32_e64 v81, v81, v195, s[24:25]
	v_mov_b32_e32 v82, 0xf149f2ca
	v_mov_b32_e32 v87, 0xf149f2ca
	v_add_f32_e32 v196, v89, v196
	v_cndmask_b32_e64 v87, v87, v196, s[94:95]
	v_add_f32_e32 v197, v73, v197
	v_cndmask_b32_e64 v82, v82, v197, s[26:27]
	v_mov_b32_e32 v83, 0xf149f2ca
	v_mov_b32_e32 v89, 0xf149f2ca
	v_add_f32_e32 v198, v90, v198
	v_cndmask_b32_e64 v89, v89, v198, s[60:61]
	v_add_f32_e32 v199, v74, v199
	v_cndmask_b32_e64 v83, v83, v199, s[28:29]
	v_mov_b32_e32 v73, 0xf149f2ca
	v_mov_b32_e32 v86, 0xf149f2ca
	v_add_f32_e32 v200, v91, v200
	v_cndmask_b32_e64 v86, v86, v200, s[62:63]
	v_add_f32_e32 v201, v75, v201
	v_cndmask_b32_e64 v73, v73, v201, s[30:31]
	v_mov_b32_e32 v72, 0xf149f2ca
	v_mov_b32_e32 v88, 0xf149f2ca
	v_add_f32_e32 v202, v92, v202
	v_cndmask_b32_e64 v88, v88, v202, s[66:67]
	v_add_f32_e32 v203, v76, v203
	v_cndmask_b32_e64 v72, v72, v203, s[34:35]
	v_mov_b32_e32 v71, 0xf149f2ca
	v_mov_b32_e32 v76, 0xf149f2ca
	v_add_f32_e32 v204, v93, v204
	v_cndmask_b32_e64 v76, v76, v204, s[58:59]
	v_add_f32_e32 v205, v77, v205
	v_cndmask_b32_e64 v71, v71, v205, s[36:37]
	v_mov_b32_e32 v74, 0xf149f2ca
	v_mov_b32_e32 v77, 0xf149f2ca
	v_add_f32_e32 v206, v94, v206
	v_cndmask_b32_e64 v77, v77, v206, s[44:45]
	v_add_f32_e32 v207, v78, v207
	v_cndmask_b32_e64 v74, v74, v207, s[38:39]
	v_mov_b32_e32 v75, 0xf149f2ca
	v_mov_b32_e32 v78, 0xf149f2ca
	v_add_f32_e32 v208, v95, v208
	v_cndmask_b32_e64 v78, v78, v208, s[48:49]
	v_add_f32_e32 v209, v79, v209
	v_cndmask_b32_e64 v75, v75, v209, s[40:41]
	s_and_saveexec_b64 s[56:57], s[14:15]
	s_xor_b64 s[56:57], exec, s[56:57]
	s_cbranch_execz .LBB0_1012
	v_max_f32_e32 v64, v80, v80
	v_max_f32_e32 v79, v148, v148
	v_max_f32_e32 v64, v79, v64
	v_max_f32_e32 v79, v65, v65
	v_max_f32_e32 v90, v149, v149
	v_max_f32_e32 v79, v90, v79
	v_max_f32_e32 v90, v66, v66
	v_max_f32_e32 v91, v150, v150
	v_max3_f32 v64, v147, v146, v64
	v_max_f32_e32 v90, v91, v90
	v_max3_f32 v64, v64, v79, v90
	v_max_f32_e32 v79, v67, v67
	v_max_f32_e32 v90, v151, v151
	v_max_f32_e32 v79, v90, v79
	v_max_f32_e32 v90, v68, v68
	v_max_f32_e32 v91, v84, v84
	v_max_f32_e32 v90, v91, v90
	v_max3_f32 v64, v64, v79, v90
	v_max_f32_e32 v79, v69, v69
	v_max_f32_e32 v90, v152, v152
	v_max_f32_e32 v79, v90, v79
	v_max_f32_e32 v90, v70, v70
	v_max_f32_e32 v91, v153, v153
	v_max_f32_e32 v90, v91, v90
	v_max3_f32 v64, v64, v79, v90
	v_max_f32_e32 v79, v81, v81
	v_max_f32_e32 v90, v85, v85
	v_max_f32_e32 v79, v90, v79
	v_max_f32_e32 v90, v82, v82
	v_max_f32_e32 v91, v87, v87
	v_max_f32_e32 v90, v91, v90
	v_max3_f32 v64, v64, v79, v90
	v_max_f32_e32 v79, v83, v83
	v_max_f32_e32 v90, v89, v89
	v_max_f32_e32 v79, v90, v79
	v_max_f32_e32 v90, v73, v73
	v_max_f32_e32 v91, v86, v86
	v_max_f32_e32 v90, v91, v90
	v_max3_f32 v64, v64, v79, v90
	v_max_f32_e32 v79, v72, v72
	v_max_f32_e32 v90, v88, v88
	v_max_f32_e32 v79, v90, v79
	v_max_f32_e32 v90, v71, v71
	v_max_f32_e32 v91, v76, v76
	v_max_f32_e32 v90, v91, v90
	v_max3_f32 v64, v64, v79, v90
	v_max_f32_e32 v79, v74, v74
	v_max_f32_e32 v90, v77, v77
	v_max_f32_e32 v79, v90, v79
	v_max_f32_e32 v90, v75, v75
	v_max_f32_e32 v91, v78, v78
	v_max_f32_e32 v90, v91, v90
	v_max3_f32 v64, v64, v79, v90
	v_mbcnt_lo_u32_b32 v79, -1, 0
	v_mbcnt_hi_u32_b32 v79, -1, v79
	s_nop 0
	v_lshlrev_b32_e32 v79, 2, v79
	v_xor_b32_e32 v79, 0x80, v79
	ds_bpermute_b32 v79, v79, v64
	s_waitcnt lgkmcnt(0)
	v_max3_f32 v79, v135, v64, v79
	v_sub_f32_e32 v64, v135, v79
	v_exp_f32_e32 v64, v64
	s_nop 0
	v_cmp_neq_f32_e32 vcc, 1.0, v64
	s_cbranch_vccz .LBB0_1011
	v_pk_mul_f32 v[46:47], v[46:47], v[64:65] op_sel_hi:[1,0]
	v_pk_mul_f32 v[44:45], v[44:45], v[64:65] op_sel_hi:[1,0]
	v_pk_mul_f32 v[42:43], v[42:43], v[64:65] op_sel_hi:[1,0]
	v_pk_mul_f32 v[40:41], v[40:41], v[64:65] op_sel_hi:[1,0]
	v_pk_mul_f32 v[38:39], v[38:39], v[64:65] op_sel_hi:[1,0]
	v_pk_mul_f32 v[36:37], v[36:37], v[64:65] op_sel_hi:[1,0]
	v_pk_mul_f32 v[34:35], v[34:35], v[64:65] op_sel_hi:[1,0]
	v_pk_mul_f32 v[32:33], v[32:33], v[64:65] op_sel_hi:[1,0]
	v_pk_mul_f32 v[30:31], v[30:31], v[64:65] op_sel_hi:[1,0]
	v_pk_mul_f32 v[28:29], v[28:29], v[64:65] op_sel_hi:[1,0]
	v_pk_mul_f32 v[26:27], v[26:27], v[64:65] op_sel_hi:[1,0]
	v_pk_mul_f32 v[24:25], v[24:25], v[64:65] op_sel_hi:[1,0]
	v_pk_mul_f32 v[22:23], v[22:23], v[64:65] op_sel_hi:[1,0]
	v_pk_mul_f32 v[20:21], v[20:21], v[64:65] op_sel_hi:[1,0]
	v_pk_mul_f32 v[18:19], v[18:19], v[64:65] op_sel_hi:[1,0]
	v_pk_mul_f32 v[16:17], v[16:17], v[64:65] op_sel_hi:[1,0]
